# both sub-tiles: first map-1 PV MFMA issued after its four operand converts; the other four converts run in its shadow
# speedup vs baseline: 1.0082x; 1.0082x over previous
; #define LAS __attribute__((address_space(3)))
; #define AT_RAISE(MP) do { if (trig[MP]) { const float dl = fmaxf(__builtin_amdgcn_logf(pmx[MP]), 0.f), al = __builtin_amdgcn_exp2f(-dl); mref[MP] += dl; lsum[MP] *= al; \
;                 _Pragma("unroll") for (int cb = 0; cb < 4; ++cb) o[MP][cb] = o[MP][cb] * al; } } while (0)
; __device__ __forceinline__ void dattn_unit(LAS unsigned char* lds, int b, int h, int qb, const bf16* Q, const bf16* K, const bf16* V, bf16* YB, float lam, const float* subg, float oml, int tid) {
;     ...
;                 const LAS bf16* kp = Ks + (32 * sub + ql) * 72 + hi * 8;
;                 bf16x8 ka = *(const LAS bf16x8*)kp, kb = *(const LAS bf16x8*)(kp + 64 * 72), qa = qsp[0], qb = qsp[4 * 64];
;                 __builtin_amdgcn_sched_group_barrier(0x100, 4, 0);
; #pragma unroll
;                 for (int ks = 0; ks < 4; ++ks) { bf16x8 ka2 = ka, kb2 = kb, qa2 = qa, qb2 = qb;
;                     if (ks < 3) { ka2 = *(const LAS bf16x8*)(kp + (ks + 1) * 16); kb2 = *(const LAS bf16x8*)(kp + 64 * 72 + (ks + 1) * 16); qa2 = qsp[(ks + 1) * 64]; qb2 = qsp[(4 + ks + 1) * 64];
;     ...
;             for (int cb = 0; cb < 4; ++cb) { const LAS bf16* vp = Vt + (32 * cb + ql) * 72 + 32 * sub + 4 * hi;
;                 const v2u a0 = *(const LAS v2u*)(vp), a1 = *(const LAS v2u*)(vp + 8), a2 = *(const LAS v2u*)(vp + 16), a3 = *(const LAS v2u*)(vp + 24);
;                 const v4u f0 = {a0.x, a0.y, a1.x, a1.y}, f1 = {a2.x, a2.y, a3.x, a3.y};
;                 o[0][cb] = __builtin_amdgcn_mfma_f32_32x32x16_bf16(__builtin_bit_cast(bf16x8, f0), pA0, o[0][cb], 0, 0, 0);
;                 o[1][cb] = __builtin_amdgcn_mfma_f32_32x32x16_bf16(__builtin_bit_cast(bf16x8, f0), pA1, o[1][cb], 0, 0, 0);
;                 o[0][cb] = __builtin_amdgcn_mfma_f32_32x32x16_bf16(__builtin_bit_cast(bf16x8, f1), pB0, o[0][cb], 0, 0, 0);
;                 o[1][cb] = __builtin_amdgcn_mfma_f32_32x32x16_bf16(__builtin_bit_cast(bf16x8, f1), pB1, o[1][cb], 0, 0, 0); }
;             AT_RAISE(0); AT_RAISE(1);
.LBB0_234:
	v_cvt_pk_bf16_f32 v152, v155, v129
	v_cvt_pk_bf16_f32 v153, v130, v131
	v_cvt_pk_bf16_f32 v154, v132, v156
	v_cvt_pk_bf16_f32 v155, v157, v158
	s_andn2_b64 vcc, exec, s[48:49]
	s_nop 0
	v_mfma_f32_32x32x16_bf16 v[64:79], v[228:231], v[152:155], v[64:79]
	v_cvt_pk_bf16_f32 v130, v133, v134
	v_cvt_pk_bf16_f32 v131, v135, v136
	v_cvt_pk_bf16_f32 v132, v137, v138
	v_cvt_pk_bf16_f32 v133, v139, v140
	ds_read_b128 v[138:141], v199 offset:4608
	s_nop 0
	v_mfma_f32_32x32x16_bf16 v[64:79], v[232:235], v[130:133], v[64:79]
	v_mfma_f32_32x32x16_bf16 v[32:47], v[236:239], v[152:155], v[32:47]
	v_mfma_f32_32x32x16_bf16 v[32:47], v[240:243], v[130:133], v[32:47]
	v_mfma_f32_32x32x16_bf16 v[96:111], v[220:223], v[152:155], v[96:111]
	ds_read_b128 v[218:221], v189
	ds_read_b128 v[222:225], v189 offset:4096
	v_mfma_f32_32x32x16_bf16 v[96:111], v[204:207], v[130:133], v[96:111]
	ds_read_b128 v[204:207], v199 offset:13824
	ds_read_b128 v[226:229], v199 offset:4640
	ds_read_b128 v[230:233], v199 offset:13856
	v_mfma_f32_32x32x16_bf16 v[0:15], v[212:215], v[152:155], v[0:15]
	ds_read_b128 v[234:237], v189 offset:1024
	ds_read_b128 v[238:241], v189 offset:5120
	v_mfma_f32_32x32x16_bf16 v[0:15], v[200:203], v[130:133], v[0:15]
	s_cbranch_vccnz .LBB0_236
	v_log_f32_e32 v129, v146
	s_nop 0
	v_max_f32_e32 v129, 0, v129
	v_exp_f32_e64 v130, -v129
	v_add_f32_e32 v190, v190, v129
	s_nop 1
	v_pk_mul_f32 v[126:127], v[130:131], v[126:127] op_sel_hi:[0,1]
	v_pk_mul_f32 v[124:125], v[130:131], v[124:125] op_sel_hi:[0,1]
	v_pk_mul_f32 v[122:123], v[130:131], v[122:123] op_sel_hi:[0,1]
	v_pk_mul_f32 v[120:121], v[130:131], v[120:121] op_sel_hi:[0,1]
	v_pk_mul_f32 v[118:119], v[130:131], v[118:119] op_sel_hi:[0,1]
	v_pk_mul_f32 v[116:117], v[130:131], v[116:117] op_sel_hi:[0,1]
	v_pk_mul_f32 v[114:115], v[130:131], v[114:115] op_sel_hi:[0,1]
	v_pk_mul_f32 v[112:113], v[130:131], v[112:113] op_sel_hi:[0,1]
	v_pk_mul_f32 v[94:95], v[130:131], v[94:95] op_sel_hi:[0,1]
	v_pk_mul_f32 v[92:93], v[130:131], v[92:93] op_sel_hi:[0,1]
	v_pk_mul_f32 v[90:91], v[130:131], v[90:91] op_sel_hi:[0,1]
	v_pk_mul_f32 v[88:89], v[130:131], v[88:89] op_sel_hi:[0,1]
	v_pk_mul_f32 v[86:87], v[130:131], v[86:87] op_sel_hi:[0,1]
	v_pk_mul_f32 v[84:85], v[130:131], v[84:85] op_sel_hi:[0,1]
	v_pk_mul_f32 v[82:83], v[130:131], v[82:83] op_sel_hi:[0,1]
	v_pk_mul_f32 v[80:81], v[130:131], v[80:81] op_sel_hi:[0,1]
	v_pk_mul_f32 v[62:63], v[130:131], v[62:63] op_sel_hi:[0,1]
	v_pk_mul_f32 v[60:61], v[130:131], v[60:61] op_sel_hi:[0,1]
	v_pk_mul_f32 v[58:59], v[130:131], v[58:59] op_sel_hi:[0,1]
	v_pk_mul_f32 v[56:57], v[130:131], v[56:57] op_sel_hi:[0,1]
	v_pk_mul_f32 v[54:55], v[130:131], v[54:55] op_sel_hi:[0,1]
	v_pk_mul_f32 v[52:53], v[130:131], v[52:53] op_sel_hi:[0,1]
	v_pk_mul_f32 v[50:51], v[130:131], v[50:51] op_sel_hi:[0,1]
	v_pk_mul_f32 v[48:49], v[130:131], v[48:49] op_sel_hi:[0,1]
	v_pk_mul_f32 v[30:31], v[130:131], v[30:31] op_sel_hi:[0,1]
	v_pk_mul_f32 v[28:29], v[130:131], v[28:29] op_sel_hi:[0,1]
	v_pk_mul_f32 v[26:27], v[130:131], v[26:27] op_sel_hi:[0,1]
	v_pk_mul_f32 v[24:25], v[130:131], v[24:25] op_sel_hi:[0,1]
	v_pk_mul_f32 v[22:23], v[130:131], v[22:23] op_sel_hi:[0,1]
	v_pk_mul_f32 v[20:21], v[130:131], v[20:21] op_sel_hi:[0,1]
	v_pk_mul_f32 v[18:19], v[130:131], v[18:19] op_sel_hi:[0,1]
	v_pk_mul_f32 v[16:17], v[130:131], v[16:17] op_sel_hi:[0,1]
	v_mul_f32_e32 v179, v179, v130

; #define LAS __attribute__((address_space(3)))
; #define AT_RAISE(MP) do { if (trig[MP]) { const float dl = fmaxf(__builtin_amdgcn_logf(pmx[MP]), 0.f), al = __builtin_amdgcn_exp2f(-dl); mref[MP] += dl; lsum[MP] *= al; \
;                 _Pragma("unroll") for (int cb = 0; cb < 4; ++cb) o[MP][cb] = o[MP][cb] * al; } } while (0)
; __device__ __forceinline__ void dattn_unit(LAS unsigned char* lds, int b, int h, int qb, const bf16* Q, const bf16* K, const bf16* V, bf16* YB, float lam, const float* subg, float oml, int tid) {
;     ...
;             for (int cb = 0; cb < 4; ++cb) { const LAS bf16* vp = Vt + (32 * cb + ql) * 72 + 32 * sub + 4 * hi;
;                 const v2u a0 = *(const LAS v2u*)(vp), a1 = *(const LAS v2u*)(vp + 8), a2 = *(const LAS v2u*)(vp + 16), a3 = *(const LAS v2u*)(vp + 24);
;                 const v4u f0 = {a0.x, a0.y, a1.x, a1.y}, f1 = {a2.x, a2.y, a3.x, a3.y};
;                 o[0][cb] = __builtin_amdgcn_mfma_f32_32x32x16_bf16(__builtin_bit_cast(bf16x8, f0), pA0, o[0][cb], 0, 0, 0);
;                 o[1][cb] = __builtin_amdgcn_mfma_f32_32x32x16_bf16(__builtin_bit_cast(bf16x8, f0), pA1, o[1][cb], 0, 0, 0);
;                 o[0][cb] = __builtin_amdgcn_mfma_f32_32x32x16_bf16(__builtin_bit_cast(bf16x8, f1), pB0, o[0][cb], 0, 0, 0);
;                 o[1][cb] = __builtin_amdgcn_mfma_f32_32x32x16_bf16(__builtin_bit_cast(bf16x8, f1), pB1, o[1][cb], 0, 0, 0); }
;             AT_RAISE(0); AT_RAISE(1);
;         }
;     ...
;         }
;         if (t + 1 < NT) AT_STAGE((t + 1) & 1);
.LBB0_245:
	v_cvt_pk_bf16_f32 v152, v155, v129
	v_cvt_pk_bf16_f32 v153, v130, v131
	v_cvt_pk_bf16_f32 v154, v132, v156
	v_cvt_pk_bf16_f32 v155, v157, v158
	s_xor_b32 s18, s38, 0x9000
	v_add3_u32 v148, s18, v196, v180
	v_add3_u32 v149, s18, v197, v195
	s_andn2_b64 vcc, exec, s[48:49]
	s_nop 0
	v_mfma_f32_32x32x16_bf16 v[64:79], v[222:225], v[152:155], v[64:79]
	v_cvt_pk_bf16_f32 v130, v133, v134
	v_cvt_pk_bf16_f32 v131, v135, v136
	v_cvt_pk_bf16_f32 v132, v137, v138
	v_cvt_pk_bf16_f32 v133, v139, v140
	s_waitcnt vmcnt(3)
	ds_write_b128 v148, v[168:171]
	ds_read_b128 v[204:207], v189
	v_mfma_f32_32x32x16_bf16 v[64:79], v[226:229], v[130:133], v[64:79]
	s_waitcnt vmcnt(2)
	ds_write_b128 v148, v[172:175] offset:9216
	v_mfma_f32_32x32x16_bf16 v[32:47], v[230:233], v[152:155], v[32:47]
	ds_read_b128 v[230:233], v189 offset:1024
	s_waitcnt vmcnt(1)
	ds_write_b16 v149, v164 offset:18432
	ds_write_b16_d16_hi v149, v164 offset:18576
	ds_write_b16 v149, v165 offset:18720
	v_mfma_f32_32x32x16_bf16 v[32:47], v[234:237], v[130:133], v[32:47]
	ds_read_b128 v[234:237], v189 offset:5120
	ds_write_b16_d16_hi v149, v165 offset:18864
	ds_write_b16 v149, v166 offset:19008
	ds_write_b16_d16_hi v149, v166 offset:19152
	v_mfma_f32_32x32x16_bf16 v[96:111], v[212:215], v[152:155], v[96:111]
	ds_write_b16 v149, v167 offset:19296
	ds_write_b16_d16_hi v149, v167 offset:19440
	s_waitcnt vmcnt(0)
	ds_write_b16 v149, v160 offset:19584
	v_mfma_f32_32x32x16_bf16 v[96:111], v[200:203], v[130:133], v[96:111]
	ds_write_b16_d16_hi v149, v160 offset:19728
	ds_write_b16 v149, v161 offset:19872
	ds_write_b16_d16_hi v149, v161 offset:20016
	v_mfma_f32_32x32x16_bf16 v[0:15], v[238:241], v[152:155], v[0:15]
	ds_write_b16 v149, v162 offset:20160
	ds_write_b16_d16_hi v149, v162 offset:20304
	v_mfma_f32_32x32x16_bf16 v[0:15], v[218:221], v[130:133], v[0:15]
	ds_read_b128 v[218:221], v189 offset:4096
	ds_write_b16 v149, v163 offset:20448
	ds_write_b16_d16_hi v149, v163 offset:20592
	s_cbranch_vccnz .LBB0_247
	v_log_f32_e32 v129, v146
	s_nop 0
	v_max_f32_e32 v129, 0, v129
	v_exp_f32_e64 v130, -v129
	v_add_f32_e32 v190, v190, v129
	s_nop 1
	v_pk_mul_f32 v[126:127], v[130:131], v[126:127] op_sel_hi:[0,1]
	v_pk_mul_f32 v[124:125], v[130:131], v[124:125] op_sel_hi:[0,1]
	v_pk_mul_f32 v[122:123], v[130:131], v[122:123] op_sel_hi:[0,1]
	v_pk_mul_f32 v[120:121], v[130:131], v[120:121] op_sel_hi:[0,1]
	v_pk_mul_f32 v[118:119], v[130:131], v[118:119] op_sel_hi:[0,1]
	v_pk_mul_f32 v[116:117], v[130:131], v[116:117] op_sel_hi:[0,1]
	v_pk_mul_f32 v[114:115], v[130:131], v[114:115] op_sel_hi:[0,1]
	v_pk_mul_f32 v[112:113], v[130:131], v[112:113] op_sel_hi:[0,1]
	v_pk_mul_f32 v[94:95], v[130:131], v[94:95] op_sel_hi:[0,1]
	v_pk_mul_f32 v[92:93], v[130:131], v[92:93] op_sel_hi:[0,1]
	v_pk_mul_f32 v[90:91], v[130:131], v[90:91] op_sel_hi:[0,1]
	v_pk_mul_f32 v[88:89], v[130:131], v[88:89] op_sel_hi:[0,1]
	v_pk_mul_f32 v[86:87], v[130:131], v[86:87] op_sel_hi:[0,1]
	v_pk_mul_f32 v[84:85], v[130:131], v[84:85] op_sel_hi:[0,1]
	v_pk_mul_f32 v[82:83], v[130:131], v[82:83] op_sel_hi:[0,1]
	v_pk_mul_f32 v[80:81], v[130:131], v[80:81] op_sel_hi:[0,1]
	v_pk_mul_f32 v[62:63], v[130:131], v[62:63] op_sel_hi:[0,1]
	v_pk_mul_f32 v[60:61], v[130:131], v[60:61] op_sel_hi:[0,1]
	v_pk_mul_f32 v[58:59], v[130:131], v[58:59] op_sel_hi:[0,1]
	v_pk_mul_f32 v[56:57], v[130:131], v[56:57] op_sel_hi:[0,1]
	v_pk_mul_f32 v[54:55], v[130:131], v[54:55] op_sel_hi:[0,1]
	v_pk_mul_f32 v[52:53], v[130:131], v[52:53] op_sel_hi:[0,1]
	v_pk_mul_f32 v[50:51], v[130:131], v[50:51] op_sel_hi:[0,1]
	v_pk_mul_f32 v[48:49], v[130:131], v[48:49] op_sel_hi:[0,1]
	v_pk_mul_f32 v[30:31], v[130:131], v[30:31] op_sel_hi:[0,1]
	v_pk_mul_f32 v[28:29], v[130:131], v[28:29] op_sel_hi:[0,1]
	v_pk_mul_f32 v[26:27], v[130:131], v[26:27] op_sel_hi:[0,1]
	v_pk_mul_f32 v[24:25], v[130:131], v[24:25] op_sel_hi:[0,1]
	v_pk_mul_f32 v[22:23], v[130:131], v[22:23] op_sel_hi:[0,1]
	v_pk_mul_f32 v[20:21], v[130:131], v[20:21] op_sel_hi:[0,1]
	v_pk_mul_f32 v[18:19], v[130:131], v[18:19] op_sel_hi:[0,1]
	v_pk_mul_f32 v[16:17], v[130:131], v[16:17] op_sel_hi:[0,1]
	v_mul_f32_e32 v179, v179, v130
